# diff attention: tiles scaled against the running reference max without a per-tile row-max pass; row sum compared with e^8 selects the (validated) exact-max rescale side path; l carried as per-lane par
# speedup vs baseline: 1.0259x; 1.0066x over previous
; #define LAS __attribute__((address_space(3)))
; DI float bflo(unsigned w) { return __uint_as_float(w << 16); }
; template <int DQK, int SDEPTH, bool OUT_BF16, int QREG = DQK / 16, bool OUT_F16 = false> ...
;     ...
;   const bf16_t* Qw = Qb + (long)(wid * QBLK + r32) * DQK + hi * 8;
; #pragma unroll
;   for (int d0 = 0; d0 < QREG; ++d0) qr[d0] = *reinterpret_cast<const bf16x8*>(Qw + d0 * 16);
;   if constexpr (QLDS > 0) {
;     static_assert(DQK != 192 || QLDS >= 4, "rope fragments must be among the LDS ones");
; #pragma unroll
;     for (int d0 = QREG; d0 < (DQK == 192 ? 8 : DQK / 16); ++d0) *(LAS bf16x8*)(Qp + (d0 - QREG) * 1024) = *reinterpret_cast<const bf16x8*>(Qw + d0 * 16);
;     if constexpr (DQK == 192) {
;       u32x4 f[4];
; #pragma unroll
;       for (int d0 = 0; d0 < 4; ++d0) f[d0] = *reinterpret_cast<const u32x4*>(Qw + (8 + d0) * 16);
;       if (tq0 >= 0) { const int t = tq0 + wid * QBLK + r32; const f32x2* rr = rt + (t >> 6) * 16 + 8 * hi; const f32x2* rc = rt + (t & 63) * 16 + 8 * hi;
; #pragma unroll
;         for (int w2 = 0; w2 < 4; ++w2) { float a0 = bflo(f[0][w2]), a1 = bfhi(f[0][w2]), b0 = bflo(f[1][w2]), b1 = bfhi(f[1][w2]), c0 = bflo(f[2][w2]), c1 = bfhi(f[2][w2]), e0 = bflo(f[3][w2]), e1 = bfhi(f[3][w2]);
;           const f32x2 r0 = rr[2 * w2], r1 = rr[2 * w2 + 1], s0 = rc[2 * w2], s1 = rc[2 * w2 + 1];
;           f[0][w2] = cvtpk(a0 * r0.x - b0 * r0.y, a1 * r1.x - b1 * r1.y); f[1][w2] = cvtpk(a0 * r0.y + b0 * r0.x, a1 * r1.y + b1 * r1.x);
;           f[2][w2] = cvtpk(c0 * s0.x - e0 * s0.y, c1 * s1.x - e1 * s1.y); f[3][w2] = cvtpk(c0 * s0.y + e0 * s0.x, c1 * s1.y + e1 * s1.x); } }
; #pragma unroll
;       for (int d0 = 0; d0 < 4; ++d0) *(LAS u32x4*)(Qp + (8 - QREG + d0) * 1024) = f[d0];
;     }
;   }
;     ...
;   const int sr = tid >> 4, sc = (tid & 15) * 8, vst0 = v_st(sr, sc), vst1 = v_st(32 + sr, sc);
;   int krow[NKC], kcol[NKC];
; #pragma unroll
;   for (int i = 0; i < NKC; ++i) { const int ci = tid + i * 512; krow[i] = ci / CPR; kcol[i] = (ci % CPR) * 8; }
;   const int vb0 = (int)(uintptr_t)V_lds + v_rd_base(lane);
;   struct { bf16x8 vs0, vs1, ks[NKC]; } sr_[SDEPTH];
;     ...
;   f32x16 pA0, pA1, pB0, pB1; float mnA, mnB, alA, alB; bf16x8 pa0, pa1, pa2, pa3; const int NT = seq / KVBLK;
;   constexpr int SE = 0, SO = SDEPTH - 1;
;   SLOAD(SE, 0); asm volatile("s_waitcnt vmcnt(0)" ::: "memory"); SWRITE(0, SE); __syncthreads();
.LBB0_781:
	s_add_i32 s2, s0, 0x100
	s_ashr_i32 s3, s2, 31
	s_and_b64 s[0:1], s[42:43], exec
	s_cselect_b32 s3, 0, s3
	s_cselect_b32 s2, 0, s2
	s_cmp_eq_u32 s8, 1
	s_cselect_b64 s[40:41], -1, 0
	s_and_b64 s[0:1], s[40:41], exec
	s_mul_i32 s10, s24, 0x2100
	s_cselect_b32 s28, 0x1080, 0
	s_mul_hi_i32 s8, s24, 0x2100
	s_add_u32 s0, s2, s10
	s_addc_u32 s1, s3, s8
	s_lshl_b64 s[0:1], s[0:1], 7
	s_add_u32 s0, s4, s0
	s_addc_u32 s1, s5, s1
	s_add_u32 s2, s10, s28
	s_addc_u32 s3, s8, 0
	s_lshl_b64 s[2:3], s[2:3], 7
	s_add_u32 s2, s4, s2
	s_addc_u32 s3, s5, s3
	s_mul_i32 s10, s25, 0x2100
	s_mul_hi_i32 s8, s25, 0x2100
	s_add_u32 s10, s10, s28
	s_addc_u32 s11, s8, 0
	s_lshl_b64 s[10:11], s[10:11], 8
	v_ashrrev_i32_e32 v4, 31, v2
	s_add_u32 s8, s4, s10
	v_lshrrev_b32_e32 v4, 29, v4
	s_addc_u32 s11, s5, s11
	v_ashrrev_i32_e32 v16, 4, v2
	v_add_u32_e32 v4, v2, v4
	s_add_u32 s10, s8, 0x37404000
	v_lshlrev_b32_e32 v3, 3, v58
	v_ashrrev_i32_e32 v20, 3, v4
	v_and_b32_e32 v4, -8, v4
	v_ashrrev_i32_e32 v17, 31, v16
	s_addc_u32 s11, s11, 0
	v_and_b32_e32 v0, 0x78, v3
	v_add_u32_e32 v18, 32, v16
	v_sub_u32_e32 v26, v2, v4
	v_lshlrev_b64 v[50:51], 8, v[16:17]
	v_lshlrev_b32_e32 v12, 3, v26
	v_lshl_add_u64 v[4:5], s[10:11], 0, v[50:51]
	v_lshlrev_b32_e32 v6, 1, v0
	v_mov_b32_e32 v7, v1
	v_ashrrev_i32_e32 v19, 31, v18
	v_ashrrev_i32_e32 v21, 31, v20
	v_lshl_add_u64 v[56:57], v[4:5], 0, v[6:7]
	v_lshlrev_b64 v[4:5], 8, v[18:19]
	v_ashrrev_i32_e32 v13, 31, v12
	v_lshlrev_b64 v[52:53], 7, v[20:21]
	v_lshl_add_u64 v[4:5], s[10:11], 0, v[4:5]
	v_lshl_add_u64 v[14:15], s[2:3], 0, v[52:53]
	v_lshlrev_b64 v[54:55], 1, v[12:13]
	v_lshl_add_u64 v[8:9], v[4:5], 0, v[6:7]
	v_lshl_add_u64 v[76:77], v[14:15], 0, v[54:55]
	s_mov_b32 s2, 0x36384000
	global_load_dwordx4 v[4:7], v[56:57], off
	s_nop 0
	global_load_dwordx4 v[8:11], v[8:9], off
	v_add_co_u32_e32 v12, vcc, s2, v76
	v_ashrrev_i32_e32 v17, 1, v2
	s_movk_i32 s2, 0xffe0
	v_addc_co_u32_e32 v13, vcc, 0, v77, vcc
	v_bfi_b32 v154, s2, v17, v58
	global_load_dwordx4 v[12:15], v[12:13], off
	v_ashrrev_i32_e32 v155, 31, v154
	v_bfe_u32 v166, v58, 5, 1
	v_lshlrev_b64 v[22:23], 7, v[154:155]
	v_lshl_add_u64 v[22:23], s[0:1], 0, v[22:23]
	v_lshlrev_b32_e32 v0, 4, v166
	v_lshl_add_u64 v[22:23], v[22:23], 0, v[0:1]
	s_mov_b32 s0, 0x35304000
	v_add_co_u32_e32 v24, vcc, s0, v22
	s_mov_b64 s[0:1], 0x35304000
	s_nop 0
	v_addc_co_u32_e32 v25, vcc, 0, v23, vcc
	global_load_dwordx4 v[110:113], v[24:25], off
	v_lshl_add_u64 v[22:23], v[22:23], 0, s[0:1]
	global_load_dwordx4 v[106:109], v[22:23], off offset:32
	global_load_dwordx4 v[102:105], v[22:23], off offset:64
	global_load_dwordx4 v[98:101], v[22:23], off offset:96
	v_and_b32_e32 v19, 0xfffff0, v16
	v_lshlrev_b32_e32 v21, 1, v16
	v_and_or_b32 v19, v21, 8, v19
	v_lshrrev_b32_e32 v24, 1, v16
	v_bfe_u32 v3, v3, 5, 2
	v_and_b32_e32 v16, 3, v16
	v_and_b32_e32 v21, 0xfffff0, v18
	v_lshlrev_b32_e32 v18, 1, v18
	v_lshrrev_b32_e32 v19, 1, v19
	v_lshlrev_b32_e32 v59, 4, v58
	v_and_or_b32 v16, v24, 4, v16
	v_and_or_b32 v18, v18, 8, v21
	v_or_b32_e32 v19, v19, v3
	v_and_b32_e32 v25, 48, v59
	v_lshlrev_b32_e32 v16, 6, v16
	v_lshrrev_b32_e32 v18, 1, v18
	v_lshlrev_b32_e32 v19, 9, v19
	v_or_b32_e32 v3, v18, v3
	v_or3_b32 v18, v19, v16, v25
	v_lshlrev_b32_e32 v3, 9, v3
	v_add_u32_e32 v172, 0, v18
	v_or3_b32 v3, v3, v16, v25
	s_waitcnt vmcnt(0)
	v_add_u32_e32 v173, 0, v3
	v_lshlrev_b32_e32 v3, 7, v20
	v_and_b32_e32 v167, 31, v58
	s_movk_i32 s0, 0x70
	v_and_b32_e32 v2, 0x3fffffc0, v2
	v_lshl_add_u32 v157, v2, 2, 0
	v_and_b32_e32 v78, 63, v58
	s_mul_hi_i32 s3, s25, 0x210000
	s_mul_i32 s25, s25, 0x210000
	s_mov_b32 s8, s9
	v_and_b32_e32 v156, 0xffffffe0, v17
	s_mov_b32 s10, s9
	s_mov_b32 s11, s9
	s_mov_b32 s12, s9
	s_mov_b32 s13, s9
	s_mov_b32 s14, s9
	s_mov_b32 s15, s9
	s_mov_b32 s16, s9
	s_mov_b32 s17, s9
	s_mov_b32 s18, s9
	s_mov_b32 s19, s9
	s_mov_b32 s20, s9
	s_mov_b32 s21, s9
	s_mov_b32 s22, s9
	s_mov_b32 s23, s9
	s_mov_b32 s46, 1
	v_lshl_add_u32 v168, v167, 2, v157
	v_mov_b32_e32 v170, 0
	s_waitcnt vmcnt(6)
	ds_write_b128 v172, v[4:7]
	v_bitop3_b32 v4, v20, v26, 7 bitop3:0x6c
	v_lshl_add_u32 v4, v4, 4, 0
	v_add_u32_e32 v174, v4, v3
	s_waitcnt vmcnt(5)
	ds_write_b128 v173, v[8:11]
	v_bitop3_b32 v3, v0, v59, s0 bitop3:0x78
	s_movk_i32 s0, 0x4000
	v_add_co_u32_e32 v2, vcc, s0, v56
	s_waitcnt vmcnt(4)
	ds_write_b128 v174, v[12:15] offset:32768
	v_lshl_add_u32 v12, v167, 7, 0
	v_add_u32_e32 v175, v12, v3
	s_waitcnt lgkmcnt(0)
	s_barrier
; #define SLOAD(i, k0) do { sr_[i].vs0 = *reinterpret_cast<const bf16x8*>(&Vh[(long)((k0) + sr) * DV + sc]); sr_[i].vs1 = *reinterpret_cast<const bf16x8*>(&Vh[(long)((k0) + 32 + sr) * DV + sc]); \
;     _Pragma("unroll") for (int _c = 0; _c < NKC; ++_c) sr_[i].ks[_c] = *reinterpret_cast<const bf16x8*>(&Kh[(long)((k0) + krow[_c]) * DQK + kcol[_c]]); } while (0)
; #define SWRITE(b, i) do { *(LAS bf16x8*)(V_lds + (b) * SHM_V + vst0) = sr_[i].vs0; *(LAS bf16x8*)(V_lds + (b) * SHM_V + vst1) = sr_[i].vs1; \
;     _Pragma("unroll") for (int _c = 0; _c < NKC; ++_c) *(LAS bf16x8*)(K_lds + (b) * SHM_K + kswz<DQK>(krow[_c], kcol[_c] * 2)) = sr_[i].ks[_c]; } while (0)
; #define SWAIT() do { if constexpr (SDEPTH == 2) { if constexpr (NKC == 1) asm volatile("s_waitcnt vmcnt(3)" ::: "memory"); else if constexpr (NKC == 2) asm volatile("s_waitcnt vmcnt(4)" ::: "memory"); else asm volatile("s_waitcnt vmcnt(5)" ::: "memory"); } \
;     else asm volatile("s_waitcnt vmcnt(0)" ::: "memory"); } while (0)
; DI void partialSM(f32x16& p0, f32x16& p1, float& m_reg, float& mn, float& alpha, const float SCALE) {
;   const float C = SCALE * 1.4426950408889634f;
;   float pmax = p0[0];
; #pragma unroll
;   for (int r = 1; r < 16; ++r) pmax = fmaxf(pmax, p0[r]);
; #pragma unroll
;   for (int r = 0; r < 16; ++r) pmax = fmaxf(pmax, p1[r]);
;   { auto rr = __builtin_amdgcn_permlane32_swap(__float_as_uint(pmax), __float_as_uint(pmax), false, false);
;     pmax = fmaxf(__uint_as_float(rr[0]), __uint_as_float(rr[1])); }
;   if (__builtin_expect(__all(pmax - m_reg <= THR / SCALE), 1)) { mn = m_reg; alpha = 1.f; }
;   else { mn = fmaxf(m_reg, pmax); alpha = __builtin_amdgcn_exp2f((m_reg - mn) * C); m_reg = mn; }
;   const float mnC = -mn * C;
; #pragma unroll
;   for (int r = 0; r < 16; ++r) p0[r] = fmaf(p0[r], C, mnC);
; #pragma unroll
;   for (int r = 0; r < 16; ++r) p1[r] = fmaf(p1[r], C, mnC);
; #pragma unroll
;   for (int r = 0; r < 16; ++r) p0[r] = __builtin_amdgcn_exp2f(p0[r]);
; }
; template <int DQK, int SDEPTH, bool OUT_BF16, int QREG = DQK / 16, bool OUT_F16 = false> ...
;     ...
;   SLOAD(SE, 0); asm volatile("s_waitcnt vmcnt(0)" ::: "memory"); SWRITE(0, SE); __syncthreads();
;   QKT(pA0, pA1, K_lds); partialSM(pA0, pA1, m_reg, mnA, alA, SCALE);
;   SLOAD(SO, KVBLK); if constexpr (SDEPTH == 2) { if (2 < NT) SLOAD(SE, 2 * KVBLK); }
;   SWAIT(); SWRITE(1, SO); __syncthreads();
	ds_read_b128 v[4:7], v175 offset:32768
	ds_read_b128 v[8:11], v175 offset:36864
	v_and_b32_e32 v13, 0x70, v59
	v_bitop3_b32 v3, v0, v13, 32 bitop3:0x36
	v_add_u32_e32 v176, v12, v3
	s_waitcnt vmcnt(3) lgkmcnt(1)
	v_mfma_f32_32x32x16_bf16 v[18:33], v[4:7], v[110:113], 0
	ds_read_b128 v[4:7], v176 offset:32768
	v_addc_co_u32_e32 v3, vcc, 0, v57, vcc
	s_movk_i32 s0, 0x6000
	v_lshlrev_b32_e32 v14, 3, v78
	s_waitcnt lgkmcnt(1)
	v_mfma_f32_32x32x16_bf16 v[34:49], v[8:11], v[110:113], 0
	ds_read_b128 v[8:11], v176 offset:36864
	s_waitcnt vmcnt(2) lgkmcnt(1)
	v_mfma_f32_32x32x16_bf16 v[18:33], v[4:7], v[106:109], v[18:33]
	v_add_co_u32_e32 v4, vcc, s0, v56
	s_mov_b32 s0, 0x36386000
	s_nop 0
	v_addc_co_u32_e32 v5, vcc, 0, v57, vcc
	v_bitop3_b32 v6, v0, v13, 64 bitop3:0x36
	global_load_dwordx4 v[60:63], v[2:3], off
	global_load_dwordx4 v[64:67], v[4:5], off
	v_add_co_u32_e32 v2, vcc, s0, v76
	v_add_u32_e32 v178, v12, v6
	s_nop 0
	v_addc_co_u32_e32 v3, vcc, 0, v77, vcc
	global_load_dwordx4 v[68:71], v[2:3], off
	ds_read_b128 v[2:5], v178 offset:32768
	v_and_b32_e32 v6, 0xc0, v59
	v_lshlrev_b32_e32 v7, 1, v58
	s_waitcnt lgkmcnt(1)
	v_mfma_f32_32x32x16_bf16 v[34:49], v[8:11], v[106:109], v[34:49]
	v_and_or_b32 v6, v14, 24, v6
	v_and_b32_e32 v7, 32, v7
	v_and_b32_e32 v8, 0x100, v14
	s_movk_i32 s0, 0x60
	v_or3_b32 v59, v6, v7, v8
	ds_read_b128 v[6:9], v178 offset:36864
	v_add_u32_e32 v171, 0, v59
	s_waitcnt vmcnt(4) lgkmcnt(1)
	v_mfma_f32_32x32x16_bf16 v[18:33], v[2:5], v[102:105], v[18:33]
	v_bitop3_b32 v2, v0, v13, s0 bitop3:0x36
	v_add_u32_e32 v177, v12, v2
	ds_read_b128 v[2:5], v177 offset:32768
	ds_read_b128 v[72:75], v177 offset:36864
	s_mov_b32 s0, 0x8000
	s_waitcnt lgkmcnt(2)
	v_mfma_f32_32x32x16_bf16 v[34:49], v[6:9], v[102:105], v[34:49]
	s_waitcnt vmcnt(3) lgkmcnt(1)
	v_mfma_f32_32x32x16_bf16 v[18:33], v[2:5], v[98:101], v[18:33]
	v_mov_b64_e32 v[2:3], s[8:9]
	v_mov_b64_e32 v[4:5], s[10:11]
	v_mov_b64_e32 v[6:7], s[12:13]
	v_mov_b64_e32 v[8:9], s[14:15]
	v_mov_b64_e32 v[10:11], s[16:17]
	v_mov_b64_e32 v[12:13], s[18:19]
	v_mov_b64_e32 v[14:15], s[20:21]
	s_waitcnt lgkmcnt(0)
	v_mfma_f32_32x32x16_bf16 v[34:49], v[72:75], v[98:101], v[34:49]
	s_nop 2
	v_max_f32_e32 v72, v19, v19
	v_max_f32_e32 v73, v18, v18
	v_max_f32_e32 v72, v73, v72
	v_max3_f32 v72, v72, v20, v21
	v_max3_f32 v72, v72, v22, v23
	v_max3_f32 v72, v72, v24, v25
	v_max3_f32 v72, v72, v26, v27
	v_max3_f32 v72, v72, v28, v29
	v_max3_f32 v72, v72, v30, v31
	v_max3_f32 v72, v72, v32, v33
	v_max3_f32 v72, v72, v34, v35
	v_max3_f32 v72, v72, v36, v37
	v_max3_f32 v72, v72, v38, v39
	v_max3_f32 v72, v72, v40, v41
	v_max3_f32 v72, v72, v42, v43
	v_max3_f32 v72, v72, v44, v45
	v_max3_f32 v72, v72, v46, v47
	v_max3_f32 v72, v72, v48, v49
	v_mov_b32_e32 v73, v72
	s_nop 1
	v_permlane32_swap_b32_e32 v72, v73
	v_max_f32_e32 v73, v73, v73
	v_max_f32_e32 v72, v72, v72
	v_max_f32_e32 v74, v72, v73
	v_add_f32_e32 v72, 0x7149f2ca, v74
	v_cmp_ge_f32_e32 vcc, s26, v72
	v_add_co_u32_e64 v72, s[0:1], s0, v56
	s_cmp_eq_u64 vcc, exec
	s_nop 0
	v_addc_co_u32_e64 v73, s[0:1], 0, v57, s[0:1]
	s_mov_b32 s0, 0xa000
	s_nop 0
	v_add_co_u32_e64 v56, s[0:1], s0, v56
	global_load_dwordx4 v[114:117], v[72:73], off
	s_nop 0
	v_addc_co_u32_e64 v57, s[0:1], 0, v57, s[0:1]
	s_mov_b32 s0, 0x36388000
	s_nop 0
	v_add_co_u32_e64 v72, s[0:1], s0, v76
	s_cselect_b64 vcc, -1, 0
	s_nop 0
	v_addc_co_u32_e64 v73, s[0:1], 0, v77, s[0:1]
	global_load_dwordx4 v[118:121], v[56:57], off
	global_load_dwordx4 v[122:125], v[72:73], off
	v_max_f32_e32 v56, 0xf149f2ca, v74
	v_cndmask_b32_e32 v142, v56, v239, vcc
	v_sub_f32_e32 v57, 0xf149f2ca, v56
	v_mul_f32_e32 v56, 0xbe38aa3b, v142
	v_fmamk_f32 v18, v18, 0x3e38aa3b, v56
	v_exp_f32_e32 v146, v18
	v_fmamk_f32 v18, v19, 0x3e38aa3b, v56
	v_exp_f32_e32 v148, v18
	v_fmamk_f32 v18, v20, 0x3e38aa3b, v56
	v_exp_f32_e32 v150, v18
	v_fmamk_f32 v18, v21, 0x3e38aa3b, v56
	v_exp_f32_e32 v152, v18
	v_fmamk_f32 v18, v22, 0x3e38aa3b, v56
	v_exp_f32_e32 v162, v18
	v_fmamk_f32 v18, v23, 0x3e38aa3b, v56
	v_exp_f32_e32 v164, v18
	v_fmamk_f32 v18, v24, 0x3e38aa3b, v56
	v_exp_f32_e32 v165, v18
	v_fmamk_f32 v18, v25, 0x3e38aa3b, v56
	v_exp_f32_e32 v186, v18
	v_fmamk_f32 v18, v26, 0x3e38aa3b, v56
	v_mul_f32_e32 v57, 0x3e38aa3b, v57
	v_exp_f32_e32 v144, v18
	v_fmamk_f32 v18, v27, 0x3e38aa3b, v56
	s_add_i32 s2, 0, 0x4000
	v_exp_f32_e32 v57, v57
	v_exp_f32_e32 v145, v18
	v_fmamk_f32 v18, v28, 0x3e38aa3b, v56
	v_add_u32_e32 v169, s2, v59
	s_lshl_b32 s2, s28, 8
	v_exp_f32_e32 v147, v18
	v_fmamk_f32 v18, v29, 0x3e38aa3b, v56
	s_add_u32 s2, s25, s2
	v_exp_f32_e32 v149, v18
	v_fmamk_f32 v18, v30, 0x3e38aa3b, v56
	s_addc_u32 s3, s3, 0
	v_mov_b64_e32 v[16:17], s[22:23]
	v_exp_f32_e32 v151, v18
	v_fmamk_f32 v18, v31, 0x3e38aa3b, v56
	v_lshl_add_u64 v[158:159], s[2:3], 0, v[50:51]
	s_mul_i32 s2, s24, 0x108000
	s_lshl_b32 s8, s28, 7
	v_pk_fma_f32 v[126:127], v[48:49], s[34:35], v[56:57] op_sel_hi:[1,0,0]
	v_pk_fma_f32 v[132:133], v[46:47], s[34:35], v[56:57] op_sel_hi:[1,0,0]
	v_pk_fma_f32 v[136:137], v[44:45], s[34:35], v[56:57] op_sel_hi:[1,0,0]
	v_pk_fma_f32 v[128:129], v[42:43], s[34:35], v[56:57] op_sel_hi:[1,0,0]
	v_pk_fma_f32 v[130:131], v[40:41], s[34:35], v[56:57] op_sel_hi:[1,0,0]
	v_pk_fma_f32 v[134:135], v[38:39], s[34:35], v[56:57] op_sel_hi:[1,0,0]
	v_pk_fma_f32 v[138:139], v[36:37], s[34:35], v[56:57] op_sel_hi:[1,0,0]
	v_pk_fma_f32 v[140:141], v[34:35], s[34:35], v[56:57] op_sel_hi:[1,0,0]
	v_exp_f32_e32 v153, v18
	v_fmamk_f32 v18, v32, 0x3e38aa3b, v56
	v_fmac_f32_e32 v56, 0x3e38aa3b, v33
	s_mul_hi_i32 s3, s24, 0x108000
	s_add_u32 s2, s2, s8
	v_exp_f32_e32 v163, v18
	v_exp_f32_e32 v183, v56
	v_and_b32_e32 v18, 15, v58
	s_addc_u32 s3, s3, 0
	s_waitcnt vmcnt(3)
	v_lshl_or_b32 v158, v18, 4, v158
	v_lshl_add_u64 v[18:19], s[2:3], 0, v[52:53]
	s_waitcnt vmcnt(5)
	ds_write_b128 v172, v[60:63] offset:16384
	s_waitcnt vmcnt(4)
	ds_write_b128 v173, v[64:67] offset:16384
	s_waitcnt vmcnt(3)
	ds_write_b128 v174, v[68:71] offset:40960
	v_cndmask_b32_e64 v179, v57, 1.0, vcc
	v_lshl_add_u64 v[160:161], v[18:19], 0, v[54:55]
	v_mov_b64_e32 v[64:65], v[16:17]
	v_mov_b64_e32 v[48:49], v[16:17]
	v_mov_b64_e32 v[32:33], v[16:17]
	v_cmp_gt_u32_e64 s[0:1], 32, v78
	v_mov_b64_e32 v[62:63], v[14:15]
	v_mov_b64_e32 v[60:61], v[12:13]
	v_mov_b64_e32 v[58:59], v[10:11]
	v_mov_b64_e32 v[56:57], v[8:9]
	v_mov_b64_e32 v[54:55], v[6:7]
	v_mov_b64_e32 v[52:53], v[4:5]
	v_mov_b64_e32 v[50:51], v[2:3]
	v_mov_b64_e32 v[46:47], v[14:15]
	v_mov_b64_e32 v[44:45], v[12:13]
	v_mov_b64_e32 v[42:43], v[10:11]
	v_mov_b64_e32 v[40:41], v[8:9]
	v_mov_b64_e32 v[38:39], v[6:7]
	v_mov_b64_e32 v[36:37], v[4:5]
	v_mov_b64_e32 v[34:35], v[2:3]
	v_mov_b64_e32 v[30:31], v[14:15]
	v_mov_b64_e32 v[28:29], v[12:13]
	v_mov_b64_e32 v[26:27], v[10:11]
	v_mov_b64_e32 v[24:25], v[8:9]
	v_mov_b64_e32 v[22:23], v[6:7]
	v_mov_b64_e32 v[20:21], v[4:5]
	v_mov_b64_e32 v[18:19], v[2:3]
	s_waitcnt lgkmcnt(0)
	s_barrier
; #define SBAR() __builtin_amdgcn_sched_barrier(0)
; #define SLOAD(i, k0) do { sr_[i].vs0 = *reinterpret_cast<const bf16x8*>(&Vh[(long)((k0) + sr) * DV + sc]); sr_[i].vs1 = *reinterpret_cast<const bf16x8*>(&Vh[(long)((k0) + 32 + sr) * DV + sc]); \
;     _Pragma("unroll") for (int _c = 0; _c < NKC; ++_c) sr_[i].ks[_c] = *reinterpret_cast<const bf16x8*>(&Kh[(long)((k0) + krow[_c]) * DQK + kcol[_c]]); } while (0)
; DI void finishSM(f32x16& p0, f32x16& p1, float alpha, float& l_reg, bf16x8& pa0, bf16x8& pa1, bf16x8& pa2, bf16x8& pa3) {
; #pragma unroll
;   for (int r = 0; r < 16; ++r) p1[r] = __builtin_amdgcn_exp2f(p1[r]);
;   float ps = 0;
; #pragma unroll
;   for (int r = 0; r < 16; ++r) ps += p0[r];
; #pragma unroll
;   for (int r = 0; r < 16; ++r) ps += p1[r];
;   { auto rr = __builtin_amdgcn_permlane32_swap(__float_as_uint(ps), __float_as_uint(ps), false, false);
;     ps = __uint_as_float(rr[0]) + __uint_as_float(rr[1]); }
;   l_reg = l_reg * alpha + ps;
;     ...
;   PK4(p0, 0, pa0); PK4(p0, 8, pa1); PK4(p1, 0, pa2); PK4(p1, 8, pa3);
; template <int DQK, int SDEPTH, bool OUT_BF16, int QREG = DQK / 16, bool OUT_F16 = false> ...
;     ...
;   for (int j = 1; j + 1 < NT; j += 2) {
;     SBAR(); QKT(pB0, pB1, K_lds + SHM_K);
;     finishSM(pA0, pA1, alA, l_reg, pa0, pa1, pa2, pa3); SBAR();
;     SLOAD(SO, (j + SDEPTH) * KVBLK); SBAR();
;     pv_d0(o, vb0, pa0, pa1, pa2, pa3); partialSM(pB0, pB1, m_reg, mnB, alB, SCALE);
	v_mov_b32_e32 v208, v146
	v_mov_b32_e32 v209, v148
	v_mov_b32_e32 v210, v150
	v_mov_b32_e32 v211, v152
	v_mov_b32_e32 v214, v162
	v_mov_b32_e32 v215, v164
	v_mov_b32_e32 v216, v165
	v_mov_b32_e32 v217, v186
	v_mov_b32_e32 v218, v144
	v_mov_b32_e32 v219, v145
	v_mov_b32_e32 v220, v147
	v_mov_b32_e32 v221, v149
	v_mov_b32_e32 v222, v151
	v_mov_b32_e32 v223, v153
	v_mov_b32_e32 v224, v163
	v_mov_b32_e32 v225, v183
	v_exp_f32_e32 v226, v140
	v_exp_f32_e32 v227, v141
	v_exp_f32_e32 v228, v138
	v_exp_f32_e32 v229, v139
	v_exp_f32_e32 v230, v134
	v_exp_f32_e32 v231, v135
	v_exp_f32_e32 v244, v130
	v_exp_f32_e32 v245, v131
	v_exp_f32_e32 v246, v128
	v_exp_f32_e32 v247, v129
	v_exp_f32_e32 v248, v136
	v_exp_f32_e32 v249, v137
	v_exp_f32_e32 v250, v132
	v_exp_f32_e32 v251, v133
	v_exp_f32_e32 v252, v126
	v_exp_f32_e32 v202, v127
	v_mov_b32_e32 v206, v142
	v_mul_f32_e32 v205, 0xbe38aa3b, v142
	v_add_f32_e32 v170, v208, v209
	v_add_f32_e32 v170, v210, v170
	v_add_f32_e32 v170, v211, v170
	v_add_f32_e32 v170, v214, v170
	v_add_f32_e32 v170, v215, v170
	v_add_f32_e32 v170, v216, v170
	v_add_f32_e32 v170, v217, v170
	v_add_f32_e32 v170, v218, v170
	v_add_f32_e32 v170, v219, v170
	v_add_f32_e32 v170, v220, v170
	v_add_f32_e32 v170, v221, v170
	v_add_f32_e32 v170, v222, v170
	v_add_f32_e32 v170, v223, v170
	v_add_f32_e32 v170, v224, v170
	v_add_f32_e32 v170, v225, v170
	v_add_f32_e32 v170, v226, v170
	v_add_f32_e32 v170, v227, v170
	v_add_f32_e32 v170, v228, v170
	v_add_f32_e32 v170, v229, v170
	v_add_f32_e32 v170, v230, v170
	v_add_f32_e32 v170, v231, v170
	v_add_f32_e32 v170, v244, v170
	v_add_f32_e32 v170, v245, v170
	v_add_f32_e32 v170, v246, v170
	v_add_f32_e32 v170, v247, v170
	v_add_f32_e32 v170, v248, v170
	v_add_f32_e32 v170, v249, v170
	v_add_f32_e32 v170, v250, v170
	v_add_f32_e32 v170, v251, v170
	v_add_f32_e32 v170, v252, v170
	v_add_f32_e32 v170, v202, v170
	s_add_u32 s80, s4, 0x37410000
	s_addc_u32 s81, s5, 0
	s_add_u32 s82, s4, 0x37412000
	s_addc_u32 s83, s5, 0
	s_add_u32 s84, s4, 0x3638a000
	s_addc_u32 s85, s5, 0
	s_add_u32 s86, s4, 0x37414000
	s_addc_u32 s87, s5, 0
	s_add_u32 s88, s4, 0x37416000
	s_addc_u32 s89, s5, 0
	s_add_u32 s90, s4, 0x3638c000
	s_addc_u32 s91, s5, 0
.LBB0_782:
	ds_read_b128 v[66:69], v175 offset:40960
	ds_read_b128 v[70:73], v175 offset:45056
	ds_read_b128 v[188:191], v176 offset:40960
	ds_read_b128 v[192:195], v176 offset:45056
	v_cvt_pk_bf16_f32 v138, v208, v209
	v_cvt_pk_bf16_f32 v139, v210, v211
	s_waitcnt lgkmcnt(3)
	v_mfma_f32_32x32x16_bf16 v[82:97], v[66:69], v[110:113], 0
	v_cvt_pk_bf16_f32 v140, v214, v215
	v_cvt_pk_bf16_f32 v141, v216, v217
	s_waitcnt lgkmcnt(2)
	v_mfma_f32_32x32x16_bf16 v[66:81], v[70:73], v[110:113], 0
	v_cvt_pk_bf16_f32 v144, v218, v219
	v_cvt_pk_bf16_f32 v145, v220, v221
	s_waitcnt lgkmcnt(1)
	v_mfma_f32_32x32x16_bf16 v[82:97], v[188:191], v[106:109], v[82:97]
	v_cvt_pk_bf16_f32 v146, v222, v223
	v_cvt_pk_bf16_f32 v147, v224, v225
	s_waitcnt lgkmcnt(0)
	v_mfma_f32_32x32x16_bf16 v[66:81], v[192:195], v[106:109], v[66:81]
	ds_read_b128 v[188:191], v178 offset:40960
	ds_read_b128 v[192:195], v178 offset:45056
	v_cvt_pk_bf16_f32 v148, v226, v227
	v_cvt_pk_bf16_f32 v149, v228, v229
	s_waitcnt lgkmcnt(1)
	v_mfma_f32_32x32x16_bf16 v[82:97], v[188:191], v[102:105], v[82:97]
	v_cvt_pk_bf16_f32 v150, v230, v231
	v_cvt_pk_bf16_f32 v151, v244, v245
	s_waitcnt lgkmcnt(0)
	v_mfma_f32_32x32x16_bf16 v[66:81], v[192:195], v[102:105], v[66:81]
	ds_read_b128 v[188:191], v177 offset:40960
	ds_read_b128 v[192:195], v177 offset:45056
	v_cvt_pk_bf16_f32 v182, v246, v247
	v_cvt_pk_bf16_f32 v183, v248, v249
	s_waitcnt lgkmcnt(1)
	v_mfma_f32_32x32x16_bf16 v[82:97], v[188:191], v[98:101], v[82:97]
	v_cvt_pk_bf16_f32 v184, v250, v251
	v_cvt_pk_bf16_f32 v185, v252, v202
	s_waitcnt lgkmcnt(0)
	v_mfma_f32_32x32x16_bf16 v[66:81], v[192:195], v[98:101], v[66:81]
	v_permlane32_swap_b32_e32 v138, v140
	v_permlane32_swap_b32_e32 v139, v141
	v_permlane32_swap_b32_e32 v144, v146
	v_permlane32_swap_b32_e32 v145, v147
	v_permlane32_swap_b32_e32 v148, v150
	v_permlane32_swap_b32_e32 v149, v151
	v_permlane32_swap_b32_e32 v182, v184
	v_permlane32_swap_b32_e32 v183, v185
	global_load_dwordx4 v[126:129], v158, s[80:81]
	global_load_dwordx4 v[130:133], v158, s[82:83]
	global_load_dwordx4 v[134:137], v160, s[84:85]
	ds_read_b64_tr_b16 v[186:187], v171 offset:0x0
	ds_read_b64_tr_b16 v[188:189], v171 offset:0x800
	ds_read_b64_tr_b16 v[190:191], v171 offset:0x1000
	ds_read_b64_tr_b16 v[192:193], v171 offset:0x1800
	ds_read_b64_tr_b16 v[194:195], v171 offset:0x2000
	ds_read_b64_tr_b16 v[196:197], v171 offset:0x2800
	ds_read_b64_tr_b16 v[198:199], v171 offset:0x3000
	ds_read_b64_tr_b16 v[200:201], v171 offset:0x3800
	s_waitcnt lgkmcnt(0)
	v_mfma_f32_32x32x16_bf16 v[2:17], v[138:141], v[186:189], v[2:17]
	ds_read_b64_tr_b16 v[186:187], v171 offset:0x200
	ds_read_b64_tr_b16 v[188:189], v171 offset:0xa00
	v_fmamk_f32 v208, v82, 0x3e38aa3b, v205
	v_fmamk_f32 v209, v83, 0x3e38aa3b, v205
	v_fmamk_f32 v210, v84, 0x3e38aa3b, v205
	v_fmamk_f32 v211, v85, 0x3e38aa3b, v205
	v_exp_f32_e32 v208, v208
	v_fmamk_f32 v214, v86, 0x3e38aa3b, v205
	v_mfma_f32_32x32x16_bf16 v[2:17], v[144:147], v[190:193], v[2:17]
	ds_read_b64_tr_b16 v[190:191], v171 offset:0x1200
	ds_read_b64_tr_b16 v[192:193], v171 offset:0x1a00
	v_exp_f32_e32 v209, v209
	v_fmamk_f32 v215, v87, 0x3e38aa3b, v205
	v_exp_f32_e32 v210, v210
	v_fmamk_f32 v216, v88, 0x3e38aa3b, v205
	v_exp_f32_e32 v211, v211
	v_fmamk_f32 v217, v89, 0x3e38aa3b, v205
	v_mfma_f32_32x32x16_bf16 v[2:17], v[148:151], v[194:197], v[2:17]
	ds_read_b64_tr_b16 v[194:195], v171 offset:0x2200
	ds_read_b64_tr_b16 v[196:197], v171 offset:0x2a00
	v_exp_f32_e32 v214, v214
	v_add_f32_e32 v180, v208, v209
	v_fmamk_f32 v218, v90, 0x3e38aa3b, v205
	v_exp_f32_e32 v215, v215
	v_add_f32_e32 v180, v210, v180
	v_fmamk_f32 v219, v91, 0x3e38aa3b, v205
	v_mfma_f32_32x32x16_bf16 v[2:17], v[182:185], v[198:201], v[2:17]
	ds_read_b64_tr_b16 v[198:199], v171 offset:0x3200
	ds_read_b64_tr_b16 v[200:201], v171 offset:0x3a00
	v_exp_f32_e32 v216, v216
	v_add_f32_e32 v180, v211, v180
	v_fmamk_f32 v220, v92, 0x3e38aa3b, v205
	v_exp_f32_e32 v217, v217
	v_add_f32_e32 v180, v214, v180
	v_fmamk_f32 v221, v93, 0x3e38aa3b, v205
	s_waitcnt lgkmcnt(0)
; #define SBAR() __builtin_amdgcn_sched_barrier(0)
; template <int OFF> DI s16x4 tr_read(int vb) { s16x4 r; asm volatile("ds_read_b64_tr_b16 %0, %1 offset:%2" : "=&v"(r) : "v"(vb), "i"(OFF) : "memory"); return r; }
; #define SWRITE(b, i) do { *(LAS bf16x8*)(V_lds + (b) * SHM_V + vst0) = sr_[i].vs0; *(LAS bf16x8*)(V_lds + (b) * SHM_V + vst1) = sr_[i].vs1; \
;     _Pragma("unroll") for (int _c = 0; _c < NKC; ++_c) *(LAS bf16x8*)(K_lds + (b) * SHM_K + kswz<DQK>(krow[_c], kcol[_c] * 2)) = sr_[i].ks[_c]; } while (0)
; #define SWAIT() do { if constexpr (SDEPTH == 2) { if constexpr (NKC == 1) asm volatile("s_waitcnt vmcnt(3)" ::: "memory"); else if constexpr (NKC == 2) asm volatile("s_waitcnt vmcnt(4)" ::: "memory"); else asm volatile("s_waitcnt vmcnt(5)" ::: "memory"); } \
;     else asm volatile("s_waitcnt vmcnt(0)" ::: "memory"); } while (0)
; template <int D0> DI void pv_one(f32x16& od, int vb, bf16x8 pa0, bf16x8 pa1, bf16x8 pa2, bf16x8 pa3) {
;   const s16x4 l0 = tr_read<v_rd_off(D0, 0, 0)>(vb), h0 = tr_read<v_rd_off(D0, 0, 1)>(vb), l1 = tr_read<v_rd_off(D0, 1, 0)>(vb), h1 = tr_read<v_rd_off(D0, 1, 1)>(vb);
;   const s16x4 l2 = tr_read<v_rd_off(D0, 2, 0)>(vb), h2 = tr_read<v_rd_off(D0, 2, 1)>(vb), l3 = tr_read<v_rd_off(D0, 3, 0)>(vb), h3 = tr_read<v_rd_off(D0, 3, 1)>(vb);
;   asm volatile("s_waitcnt lgkmcnt(0)" ::: "memory"); SBAR();
;     ...
;   od = __builtin_amdgcn_mfma_f32_32x32x16_bf16(pa0, PK(l0, h0), od, 0, 0, 0);
;   od = __builtin_amdgcn_mfma_f32_32x32x16_bf16(pa1, PK(l1, h1), od, 0, 0, 0);
;   od = __builtin_amdgcn_mfma_f32_32x32x16_bf16(pa2, PK(l2, h2), od, 0, 0, 0);
;   od = __builtin_amdgcn_mfma_f32_32x32x16_bf16(pa3, PK(l3, h3), od, 0, 0, 0);
;     ...
; }
; DI void pv_d0(f32x16* o, int vb, bf16x8 pa0, bf16x8 pa1, bf16x8 pa2, bf16x8 pa3) {
;   pv_one<0>(o[0], vb, pa0, pa1, pa2, pa3); pv_one<1>(o[1], vb, pa0, pa1, pa2, pa3); pv_one<2>(o[2], vb, pa0, pa1, pa2, pa3); pv_one<3>(o[3], vb, pa0, pa1, pa2, pa3);
; template <int DQK, int SDEPTH, bool OUT_BF16, int QREG = DQK / 16, bool OUT_F16 = false> ...
;     ...
;     pv_d0(o, vb0, pa0, pa1, pa2, pa3); partialSM(pB0, pB1, m_reg, mnB, alB, SCALE);
;     __syncthreads(); SWAIT(); SWRITE(0, SE);
;     RESC(alB); __syncthreads();
	v_mfma_f32_32x32x16_bf16 v[50:65], v[138:141], v[186:189], v[50:65]
	ds_read_b64_tr_b16 v[186:187], v171 offset:0x400
	ds_read_b64_tr_b16 v[188:189], v171 offset:0xc00
	v_exp_f32_e32 v218, v218
	v_add_f32_e32 v180, v215, v180
	v_fmamk_f32 v222, v94, 0x3e38aa3b, v205
	v_exp_f32_e32 v219, v219
	v_add_f32_e32 v180, v216, v180
	v_fmamk_f32 v223, v95, 0x3e38aa3b, v205
	v_mfma_f32_32x32x16_bf16 v[50:65], v[144:147], v[190:193], v[50:65]
	ds_read_b64_tr_b16 v[190:191], v171 offset:0x1400
	ds_read_b64_tr_b16 v[192:193], v171 offset:0x1c00
	v_exp_f32_e32 v220, v220
	v_add_f32_e32 v180, v217, v180
	v_fmamk_f32 v224, v96, 0x3e38aa3b, v205
	v_exp_f32_e32 v221, v221
	v_add_f32_e32 v180, v218, v180
	v_fmamk_f32 v225, v97, 0x3e38aa3b, v205
	v_mfma_f32_32x32x16_bf16 v[50:65], v[148:151], v[194:197], v[50:65]
	ds_read_b64_tr_b16 v[194:195], v171 offset:0x2400
	ds_read_b64_tr_b16 v[196:197], v171 offset:0x2c00
	v_exp_f32_e32 v222, v222
	v_add_f32_e32 v180, v219, v180
	v_fmamk_f32 v226, v66, 0x3e38aa3b, v205
	v_exp_f32_e32 v223, v223
	v_add_f32_e32 v180, v220, v180
	v_fmamk_f32 v227, v67, 0x3e38aa3b, v205
	v_mfma_f32_32x32x16_bf16 v[50:65], v[182:185], v[198:201], v[50:65]
	ds_read_b64_tr_b16 v[198:199], v171 offset:0x3400
	ds_read_b64_tr_b16 v[200:201], v171 offset:0x3c00
	v_exp_f32_e32 v224, v224
	v_add_f32_e32 v180, v221, v180
	v_fmamk_f32 v228, v68, 0x3e38aa3b, v205
	v_exp_f32_e32 v225, v225
	v_add_f32_e32 v180, v222, v180
	v_fmamk_f32 v229, v69, 0x3e38aa3b, v205
	s_waitcnt lgkmcnt(0)
	v_mfma_f32_32x32x16_bf16 v[34:49], v[138:141], v[186:189], v[34:49]
	ds_read_b64_tr_b16 v[186:187], v171 offset:0x600
	ds_read_b64_tr_b16 v[188:189], v171 offset:0xe00
	v_exp_f32_e32 v226, v226
	v_add_f32_e32 v180, v223, v180
	v_fmamk_f32 v230, v70, 0x3e38aa3b, v205
	v_exp_f32_e32 v227, v227
	v_add_f32_e32 v180, v224, v180
	v_fmamk_f32 v231, v71, 0x3e38aa3b, v205
	v_exp_f32_e32 v228, v228
	v_mfma_f32_32x32x16_bf16 v[34:49], v[144:147], v[190:193], v[34:49]
	ds_read_b64_tr_b16 v[190:191], v171 offset:0x1600
	ds_read_b64_tr_b16 v[192:193], v171 offset:0x1e00
	v_add_f32_e32 v180, v225, v180
	v_fmamk_f32 v244, v72, 0x3e38aa3b, v205
	v_exp_f32_e32 v229, v229
	v_add_f32_e32 v180, v226, v180
	v_fmamk_f32 v245, v73, 0x3e38aa3b, v205
	v_exp_f32_e32 v230, v230
	v_mfma_f32_32x32x16_bf16 v[34:49], v[148:151], v[194:197], v[34:49]
	ds_read_b64_tr_b16 v[194:195], v171 offset:0x2600
	ds_read_b64_tr_b16 v[196:197], v171 offset:0x2e00
	v_add_f32_e32 v180, v227, v180
	v_fmamk_f32 v246, v74, 0x3e38aa3b, v205
	v_exp_f32_e32 v231, v231
	v_add_f32_e32 v180, v228, v180
	v_fmamk_f32 v247, v75, 0x3e38aa3b, v205
	v_exp_f32_e32 v244, v244
	v_mfma_f32_32x32x16_bf16 v[34:49], v[182:185], v[198:201], v[34:49]
	ds_read_b64_tr_b16 v[198:199], v171 offset:0x3600
	ds_read_b64_tr_b16 v[200:201], v171 offset:0x3e00
	v_add_f32_e32 v180, v229, v180
	v_fmamk_f32 v248, v76, 0x3e38aa3b, v205
	v_exp_f32_e32 v245, v245
	v_add_f32_e32 v180, v230, v180
	v_fmamk_f32 v249, v77, 0x3e38aa3b, v205
	v_exp_f32_e32 v246, v246
	s_waitcnt lgkmcnt(0)
	v_mfma_f32_32x32x16_bf16 v[18:33], v[138:141], v[186:189], v[18:33]
	v_add_f32_e32 v180, v231, v180
	v_fmamk_f32 v250, v78, 0x3e38aa3b, v205
	v_exp_f32_e32 v247, v247
	v_add_f32_e32 v180, v244, v180
	v_fmamk_f32 v251, v79, 0x3e38aa3b, v205
	v_exp_f32_e32 v248, v248
	v_mfma_f32_32x32x16_bf16 v[18:33], v[144:147], v[190:193], v[18:33]
	v_add_f32_e32 v180, v245, v180
	v_fmamk_f32 v252, v80, 0x3e38aa3b, v205
	v_exp_f32_e32 v249, v249
	v_add_f32_e32 v180, v246, v180
	v_fmamk_f32 v202, v81, 0x3e38aa3b, v205
	v_exp_f32_e32 v250, v250
	v_mfma_f32_32x32x16_bf16 v[18:33], v[148:151], v[194:197], v[18:33]
	v_add_f32_e32 v180, v247, v180
	v_exp_f32_e32 v251, v251
	v_add_f32_e32 v180, v248, v180
	v_exp_f32_e32 v252, v252
	v_add_f32_e32 v180, v249, v180
	v_exp_f32_e32 v202, v202
	v_mfma_f32_32x32x16_bf16 v[18:33], v[182:185], v[198:201], v[18:33]
	v_add_f32_e32 v180, v250, v180
	v_add_f32_e32 v180, v251, v180
	v_add_f32_e32 v180, v252, v180
	v_add_f32_e32 v180, v202, v180
	v_cmp_nge_f32_e32 vcc, 0x453a4f54, v180
	v_add_f32_e32 v207, v170, v180
	s_barrier
	s_waitcnt vmcnt(3)
	ds_write_b128 v172, v[114:117]
	ds_write_b128 v173, v[118:121]
	ds_write_b128 v174, v[122:125] offset:32768
	s_cbranch_vccz .LBB0_786
; DI void partialSM(f32x16& p0, f32x16& p1, float& m_reg, float& mn, float& alpha, const float SCALE) {
;   const float C = SCALE * 1.4426950408889634f;
;   float pmax = p0[0];
; #pragma unroll
;   for (int r = 1; r < 16; ++r) pmax = fmaxf(pmax, p0[r]);
; #pragma unroll
;   for (int r = 0; r < 16; ++r) pmax = fmaxf(pmax, p1[r]);
;   { auto rr = __builtin_amdgcn_permlane32_swap(__float_as_uint(pmax), __float_as_uint(pmax), false, false);
;     pmax = fmaxf(__uint_as_float(rr[0]), __uint_as_float(rr[1])); }
;   if (__builtin_expect(__all(pmax - m_reg <= THR / SCALE), 1)) { mn = m_reg; alpha = 1.f; }
;   else { mn = fmaxf(m_reg, pmax); alpha = __builtin_amdgcn_exp2f((m_reg - mn) * C); m_reg = mn; }
;   const float mnC = -mn * C;
; #pragma unroll
;   for (int r = 0; r < 16; ++r) p0[r] = fmaf(p0[r], C, mnC);
; #pragma unroll
;   for (int r = 0; r < 16; ++r) p1[r] = fmaf(p1[r], C, mnC);
; #pragma unroll
;   for (int r = 0; r < 16; ++r) p0[r] = __builtin_amdgcn_exp2f(p0[r]);
; }
	v_max3_f32 v203, v82, v83, v84
	v_max3_f32 v204, v85, v86, v87
	v_max3_f32 v203, v203, v88, v89
	v_max3_f32 v204, v204, v90, v91
	v_max3_f32 v203, v203, v92, v93
	v_max3_f32 v204, v204, v94, v95
	v_max3_f32 v203, v203, v96, v97
	v_max3_f32 v204, v204, v66, v67
	v_max3_f32 v203, v203, v68, v69
	v_max3_f32 v204, v204, v70, v71
	v_max3_f32 v203, v203, v72, v73
	v_max3_f32 v204, v204, v74, v75
	v_max3_f32 v203, v203, v76, v77
	v_max3_f32 v204, v204, v78, v79
	v_max3_f32 v203, v203, v80, v81
	v_max_f32_e32 v203, v203, v204
	v_mov_b32_e32 v204, v203
	s_nop 1
	v_permlane32_swap_b32_e32 v203, v204
	v_max_f32_e32 v203, v203, v204
	v_max_f32_e32 v203, v206, v203
	v_sub_f32_e32 v204, v206, v203
	v_mul_f32_e32 v204, 0x3e38aa3b, v204
	v_exp_f32_e32 v182, v204
	v_mov_b32_e32 v206, v203
	v_mul_f32_e32 v205, 0xbe38aa3b, v203
	v_fmamk_f32 v208, v82, 0x3e38aa3b, v205
	v_fmamk_f32 v209, v83, 0x3e38aa3b, v205
	v_fmamk_f32 v210, v84, 0x3e38aa3b, v205
	v_fmamk_f32 v211, v85, 0x3e38aa3b, v205
	v_fmamk_f32 v214, v86, 0x3e38aa3b, v205
	v_fmamk_f32 v215, v87, 0x3e38aa3b, v205
	v_fmamk_f32 v216, v88, 0x3e38aa3b, v205
	v_fmamk_f32 v217, v89, 0x3e38aa3b, v205
	v_fmamk_f32 v218, v90, 0x3e38aa3b, v205
	v_fmamk_f32 v219, v91, 0x3e38aa3b, v205
	v_fmamk_f32 v220, v92, 0x3e38aa3b, v205
	v_fmamk_f32 v221, v93, 0x3e38aa3b, v205
	v_fmamk_f32 v222, v94, 0x3e38aa3b, v205
	v_fmamk_f32 v223, v95, 0x3e38aa3b, v205
	v_fmamk_f32 v224, v96, 0x3e38aa3b, v205
	v_fmamk_f32 v225, v97, 0x3e38aa3b, v205
	v_fmamk_f32 v226, v66, 0x3e38aa3b, v205
	v_fmamk_f32 v227, v67, 0x3e38aa3b, v205
	v_fmamk_f32 v228, v68, 0x3e38aa3b, v205
	v_fmamk_f32 v229, v69, 0x3e38aa3b, v205
	v_fmamk_f32 v230, v70, 0x3e38aa3b, v205
	v_fmamk_f32 v231, v71, 0x3e38aa3b, v205
	v_fmamk_f32 v244, v72, 0x3e38aa3b, v205
	v_fmamk_f32 v245, v73, 0x3e38aa3b, v205
	v_fmamk_f32 v246, v74, 0x3e38aa3b, v205
	v_fmamk_f32 v247, v75, 0x3e38aa3b, v205
	v_fmamk_f32 v248, v76, 0x3e38aa3b, v205
	v_fmamk_f32 v249, v77, 0x3e38aa3b, v205
	v_fmamk_f32 v250, v78, 0x3e38aa3b, v205
	v_fmamk_f32 v251, v79, 0x3e38aa3b, v205
	v_fmamk_f32 v252, v80, 0x3e38aa3b, v205
	v_fmamk_f32 v202, v81, 0x3e38aa3b, v205
	v_exp_f32_e32 v208, v208
	v_exp_f32_e32 v209, v209
	v_exp_f32_e32 v210, v210
	v_exp_f32_e32 v211, v211
	v_exp_f32_e32 v214, v214
	v_exp_f32_e32 v215, v215
	v_exp_f32_e32 v216, v216
	v_exp_f32_e32 v217, v217
	v_exp_f32_e32 v218, v218
	v_exp_f32_e32 v219, v219
	v_exp_f32_e32 v220, v220
	v_exp_f32_e32 v221, v221
	v_exp_f32_e32 v222, v222
	v_exp_f32_e32 v223, v223
	v_exp_f32_e32 v224, v224
	v_exp_f32_e32 v225, v225
	v_exp_f32_e32 v226, v226
	v_exp_f32_e32 v227, v227
	v_exp_f32_e32 v228, v228
	v_exp_f32_e32 v229, v229
	v_exp_f32_e32 v230, v230
	v_exp_f32_e32 v231, v231
	v_exp_f32_e32 v244, v244
	v_exp_f32_e32 v245, v245
	v_exp_f32_e32 v246, v246
	v_exp_f32_e32 v247, v247
	v_exp_f32_e32 v248, v248
	v_exp_f32_e32 v249, v249
	v_exp_f32_e32 v250, v250
	v_exp_f32_e32 v251, v251
	v_exp_f32_e32 v252, v252
	v_exp_f32_e32 v202, v202
	v_add_f32_e32 v180, v208, v209
	v_add_f32_e32 v180, v210, v180
	v_add_f32_e32 v180, v211, v180
	v_add_f32_e32 v180, v214, v180
	v_add_f32_e32 v180, v215, v180
	v_add_f32_e32 v180, v216, v180
	v_add_f32_e32 v180, v217, v180
	v_add_f32_e32 v180, v218, v180
	v_add_f32_e32 v180, v219, v180
	v_add_f32_e32 v180, v220, v180
	v_add_f32_e32 v180, v221, v180
	v_add_f32_e32 v180, v222, v180
	v_add_f32_e32 v180, v223, v180
	v_add_f32_e32 v180, v224, v180
	v_add_f32_e32 v180, v225, v180
	v_add_f32_e32 v180, v226, v180
	v_add_f32_e32 v180, v227, v180
	v_add_f32_e32 v180, v228, v180
	v_add_f32_e32 v180, v229, v180
	v_add_f32_e32 v180, v230, v180
	v_add_f32_e32 v180, v231, v180
	v_add_f32_e32 v180, v244, v180
	v_add_f32_e32 v180, v245, v180
	v_add_f32_e32 v180, v246, v180
	v_add_f32_e32 v180, v247, v180
	v_add_f32_e32 v180, v248, v180
	v_add_f32_e32 v180, v249, v180
	v_add_f32_e32 v180, v250, v180
	v_add_f32_e32 v180, v251, v180
	v_add_f32_e32 v180, v252, v180
	v_add_f32_e32 v180, v202, v180
	v_fma_f32 v207, v182, v170, v180
	s_and_saveexec_b64 s[10:11], s[0:1]
	ds_write_b32 v168, v182 offset:49280
	s_or_b64 exec, exec, s[10:11]
	s_waitcnt lgkmcnt(0)
	v_add_u32_e32 v139, v157, v0
	ds_read_b128 v[144:147], v139 offset:49376
	ds_read_b128 v[148:151], v139 offset:49344
	ds_read_b128 v[184:187], v139 offset:49312
	ds_read_b128 v[188:191], v139 offset:49280
	s_waitcnt lgkmcnt(3)
	v_pk_mul_f32 v[14:15], v[14:15], v[144:145]
	s_waitcnt lgkmcnt(2)
	v_pk_mul_f32 v[10:11], v[10:11], v[148:149]
	s_waitcnt lgkmcnt(1)
	v_pk_mul_f32 v[6:7], v[6:7], v[184:185]
	v_pk_mul_f32 v[16:17], v[16:17], v[146:147]
	v_pk_mul_f32 v[12:13], v[12:13], v[150:151]
	v_pk_mul_f32 v[8:9], v[8:9], v[186:187]
	s_waitcnt lgkmcnt(0)
	v_pk_mul_f32 v[4:5], v[4:5], v[190:191]
	v_pk_mul_f32 v[2:3], v[2:3], v[188:189]
	v_pk_mul_f32 v[62:63], v[62:63], v[144:145]
	v_pk_mul_f32 v[58:59], v[58:59], v[148:149]
	v_pk_mul_f32 v[54:55], v[54:55], v[184:185]
	v_pk_mul_f32 v[64:65], v[64:65], v[146:147]
	v_pk_mul_f32 v[60:61], v[60:61], v[150:151]
	v_pk_mul_f32 v[56:57], v[56:57], v[186:187]
	v_pk_mul_f32 v[52:53], v[52:53], v[190:191]
	v_pk_mul_f32 v[50:51], v[50:51], v[188:189]
	v_pk_mul_f32 v[46:47], v[46:47], v[144:145]
	v_pk_mul_f32 v[42:43], v[42:43], v[148:149]
	v_pk_mul_f32 v[38:39], v[38:39], v[184:185]
	v_pk_mul_f32 v[48:49], v[48:49], v[146:147]
	v_pk_mul_f32 v[44:45], v[44:45], v[150:151]
	v_pk_mul_f32 v[40:41], v[40:41], v[186:187]
	v_pk_mul_f32 v[36:37], v[36:37], v[190:191]
	v_pk_mul_f32 v[34:35], v[34:35], v[188:189]
	v_pk_mul_f32 v[30:31], v[30:31], v[144:145]
	v_pk_mul_f32 v[26:27], v[26:27], v[148:149]
	v_pk_mul_f32 v[22:23], v[22:23], v[184:185]
	v_pk_mul_f32 v[32:33], v[32:33], v[146:147]
	v_pk_mul_f32 v[28:29], v[28:29], v[150:151]
	v_pk_mul_f32 v[24:25], v[24:25], v[186:187]
	v_pk_mul_f32 v[20:21], v[20:21], v[190:191]
	v_pk_mul_f32 v[18:19], v[18:19], v[188:189]
; #define SBAR() __builtin_amdgcn_sched_barrier(0)
; #define SLOAD(i, k0) do { sr_[i].vs0 = *reinterpret_cast<const bf16x8*>(&Vh[(long)((k0) + sr) * DV + sc]); sr_[i].vs1 = *reinterpret_cast<const bf16x8*>(&Vh[(long)((k0) + 32 + sr) * DV + sc]); \
;     _Pragma("unroll") for (int _c = 0; _c < NKC; ++_c) sr_[i].ks[_c] = *reinterpret_cast<const bf16x8*>(&Kh[(long)((k0) + krow[_c]) * DQK + kcol[_c]]); } while (0)
; #define RESC(a) do { if (__any((a) < 1.f)) { if (hi == 0) al_l[r32] = (a); asm volatile("s_waitcnt lgkmcnt(0)" ::: "memory"); \
;     _Pragma("unroll") for (int d = 0; d < 4; ++d) _Pragma("unroll") for (int r = 0; r < 16; ++r) o[d][r] *= al_l[crow(r, hi)]; } } while (0)
; DI void finishSM(f32x16& p0, f32x16& p1, float alpha, float& l_reg, bf16x8& pa0, bf16x8& pa1, bf16x8& pa2, bf16x8& pa3) {
; #pragma unroll
;   for (int r = 0; r < 16; ++r) p1[r] = __builtin_amdgcn_exp2f(p1[r]);
;   float ps = 0;
; #pragma unroll
;   for (int r = 0; r < 16; ++r) ps += p0[r];
; #pragma unroll
;   for (int r = 0; r < 16; ++r) ps += p1[r];
;   { auto rr = __builtin_amdgcn_permlane32_swap(__float_as_uint(ps), __float_as_uint(ps), false, false);
;     ps = __uint_as_float(rr[0]) + __uint_as_float(rr[1]); }
;   l_reg = l_reg * alpha + ps;
;     ...
;   PK4(p0, 0, pa0); PK4(p0, 8, pa1); PK4(p1, 0, pa2); PK4(p1, 8, pa3);
; template <int DQK, int SDEPTH, bool OUT_BF16, int QREG = DQK / 16, bool OUT_F16 = false> ...
;     ...
;     RESC(alB); __syncthreads();
;     SBAR(); QKT(pA0, pA1, K_lds);
;     finishSM(pB0, pB1, alB, l_reg, pa0, pa1, pa2, pa3); SBAR();
;     if (SDEPTH == 1 || j + 3 < NT) SLOAD(SE, (j + 1 + SDEPTH) * KVBLK); SBAR();
;     pv_d0(o, vb0 + SHM_V, pa0, pa1, pa2, pa3); partialSM(pA0, pA1, m_reg, mnA, alA, SCALE);
.LBB0_786:
	s_waitcnt lgkmcnt(0)
	s_barrier
	ds_read_b128 v[66:69], v175 offset:32768
	ds_read_b128 v[70:73], v175 offset:36864
	ds_read_b128 v[188:191], v176 offset:32768
	ds_read_b128 v[192:195], v176 offset:36864
	v_cvt_pk_bf16_f32 v138, v208, v209
	v_cvt_pk_bf16_f32 v139, v210, v211
	s_waitcnt lgkmcnt(3)
	v_mfma_f32_32x32x16_bf16 v[82:97], v[66:69], v[110:113], 0
	v_cvt_pk_bf16_f32 v140, v214, v215
	v_cvt_pk_bf16_f32 v141, v216, v217
	s_waitcnt lgkmcnt(2)
	v_mfma_f32_32x32x16_bf16 v[66:81], v[70:73], v[110:113], 0
	v_cvt_pk_bf16_f32 v142, v218, v219
	v_cvt_pk_bf16_f32 v143, v220, v221
	s_waitcnt lgkmcnt(1)
	v_mfma_f32_32x32x16_bf16 v[82:97], v[188:191], v[106:109], v[82:97]
	v_cvt_pk_bf16_f32 v144, v222, v223
	v_cvt_pk_bf16_f32 v145, v224, v225
	s_waitcnt lgkmcnt(0)
	v_mfma_f32_32x32x16_bf16 v[66:81], v[192:195], v[106:109], v[66:81]
	ds_read_b128 v[188:191], v178 offset:32768
	ds_read_b128 v[192:195], v178 offset:36864
	v_cvt_pk_bf16_f32 v146, v226, v227
	v_cvt_pk_bf16_f32 v147, v228, v229
	s_waitcnt lgkmcnt(1)
	v_mfma_f32_32x32x16_bf16 v[82:97], v[188:191], v[102:105], v[82:97]
	v_cvt_pk_bf16_f32 v148, v230, v231
	v_cvt_pk_bf16_f32 v149, v244, v245
	s_waitcnt lgkmcnt(0)
	v_mfma_f32_32x32x16_bf16 v[66:81], v[192:195], v[102:105], v[66:81]
	ds_read_b128 v[188:191], v177 offset:32768
	ds_read_b128 v[192:195], v177 offset:36864
	v_cvt_pk_bf16_f32 v150, v246, v247
	v_cvt_pk_bf16_f32 v151, v248, v249
	s_waitcnt lgkmcnt(1)
	v_mfma_f32_32x32x16_bf16 v[82:97], v[188:191], v[98:101], v[82:97]
	v_cvt_pk_bf16_f32 v152, v250, v251
	v_cvt_pk_bf16_f32 v153, v252, v202
	s_waitcnt lgkmcnt(0)
	v_mfma_f32_32x32x16_bf16 v[66:81], v[192:195], v[98:101], v[66:81]
	v_permlane32_swap_b32_e32 v138, v140
	v_permlane32_swap_b32_e32 v139, v141
	v_permlane32_swap_b32_e32 v142, v144
	v_permlane32_swap_b32_e32 v143, v145
	v_permlane32_swap_b32_e32 v146, v148
	v_permlane32_swap_b32_e32 v147, v149
	v_permlane32_swap_b32_e32 v150, v152
	v_permlane32_swap_b32_e32 v151, v153
	s_cmp_le_u32 s7, s46
	s_cselect_b64 s[2:3], -1, 0
	s_or_b64 s[10:11], s[42:43], s[2:3]
	s_and_b64 vcc, exec, s[10:11]
	s_cbranch_vccnz .LBB0_788
	global_load_dwordx4 v[114:117], v158, s[86:87]
	global_load_dwordx4 v[118:121], v158, s[88:89]
	global_load_dwordx4 v[122:125], v160, s[90:91]
.LBB0_788:
	ds_read_b64_tr_b16 v[162:163], v169 offset:0x0
	ds_read_b64_tr_b16 v[164:165], v169 offset:0x800
	ds_read_b64_tr_b16 v[186:187], v169 offset:0x1000
	ds_read_b64_tr_b16 v[188:189], v169 offset:0x1800
	ds_read_b64_tr_b16 v[190:191], v169 offset:0x2000
	ds_read_b64_tr_b16 v[192:193], v169 offset:0x2800
	ds_read_b64_tr_b16 v[194:195], v169 offset:0x3000
	ds_read_b64_tr_b16 v[196:197], v169 offset:0x3800
	s_waitcnt lgkmcnt(0)
	v_mfma_f32_32x32x16_bf16 v[2:17], v[138:141], v[162:165], v[2:17]
	ds_read_b64_tr_b16 v[162:163], v169 offset:0x200
	ds_read_b64_tr_b16 v[164:165], v169 offset:0xa00
	v_fmamk_f32 v208, v82, 0x3e38aa3b, v205
	v_fmamk_f32 v209, v83, 0x3e38aa3b, v205
	v_fmamk_f32 v210, v84, 0x3e38aa3b, v205
	v_fmamk_f32 v211, v85, 0x3e38aa3b, v205
	v_exp_f32_e32 v208, v208
	v_fmamk_f32 v214, v86, 0x3e38aa3b, v205
	v_mfma_f32_32x32x16_bf16 v[2:17], v[142:145], v[186:189], v[2:17]
	ds_read_b64_tr_b16 v[186:187], v169 offset:0x1200
	ds_read_b64_tr_b16 v[188:189], v169 offset:0x1a00
	v_exp_f32_e32 v209, v209
	v_fmamk_f32 v215, v87, 0x3e38aa3b, v205
	v_exp_f32_e32 v210, v210
	v_fmamk_f32 v216, v88, 0x3e38aa3b, v205
	v_exp_f32_e32 v211, v211
	v_fmamk_f32 v217, v89, 0x3e38aa3b, v205
	v_mfma_f32_32x32x16_bf16 v[2:17], v[146:149], v[190:193], v[2:17]
	ds_read_b64_tr_b16 v[190:191], v169 offset:0x2200
	ds_read_b64_tr_b16 v[192:193], v169 offset:0x2a00
	v_exp_f32_e32 v214, v214
	v_add_f32_e32 v184, v208, v209
	v_fmamk_f32 v218, v90, 0x3e38aa3b, v205
	v_exp_f32_e32 v215, v215
	v_add_f32_e32 v184, v210, v184
	v_fmamk_f32 v219, v91, 0x3e38aa3b, v205
	v_mfma_f32_32x32x16_bf16 v[2:17], v[150:153], v[194:197], v[2:17]
	ds_read_b64_tr_b16 v[194:195], v169 offset:0x3200
	ds_read_b64_tr_b16 v[196:197], v169 offset:0x3a00
	v_exp_f32_e32 v216, v216
	v_add_f32_e32 v184, v211, v184
	v_fmamk_f32 v220, v92, 0x3e38aa3b, v205
	v_exp_f32_e32 v217, v217
	v_add_f32_e32 v184, v214, v184
	v_fmamk_f32 v221, v93, 0x3e38aa3b, v205
	s_waitcnt lgkmcnt(0)
	v_mfma_f32_32x32x16_bf16 v[50:65], v[138:141], v[162:165], v[50:65]
	ds_read_b64_tr_b16 v[162:163], v169 offset:0x400
	ds_read_b64_tr_b16 v[164:165], v169 offset:0xc00
	v_exp_f32_e32 v218, v218
	v_add_f32_e32 v184, v215, v184
	v_fmamk_f32 v222, v94, 0x3e38aa3b, v205
	v_exp_f32_e32 v219, v219
	v_add_f32_e32 v184, v216, v184
	v_fmamk_f32 v223, v95, 0x3e38aa3b, v205
	v_mfma_f32_32x32x16_bf16 v[50:65], v[142:145], v[186:189], v[50:65]
	ds_read_b64_tr_b16 v[186:187], v169 offset:0x1400
	ds_read_b64_tr_b16 v[188:189], v169 offset:0x1c00
	v_exp_f32_e32 v220, v220
	v_add_f32_e32 v184, v217, v184
	v_fmamk_f32 v224, v96, 0x3e38aa3b, v205
	v_exp_f32_e32 v221, v221
	v_add_f32_e32 v184, v218, v184
	v_fmamk_f32 v225, v97, 0x3e38aa3b, v205
	v_mfma_f32_32x32x16_bf16 v[50:65], v[146:149], v[190:193], v[50:65]
	ds_read_b64_tr_b16 v[190:191], v169 offset:0x2400
	ds_read_b64_tr_b16 v[192:193], v169 offset:0x2c00
	v_exp_f32_e32 v222, v222
	v_add_f32_e32 v184, v219, v184
	v_fmamk_f32 v226, v66, 0x3e38aa3b, v205
	v_exp_f32_e32 v223, v223
	v_add_f32_e32 v184, v220, v184
	v_fmamk_f32 v227, v67, 0x3e38aa3b, v205
	v_mfma_f32_32x32x16_bf16 v[50:65], v[150:153], v[194:197], v[50:65]
	ds_read_b64_tr_b16 v[194:195], v169 offset:0x3400
	ds_read_b64_tr_b16 v[196:197], v169 offset:0x3c00
	v_exp_f32_e32 v224, v224
	v_add_f32_e32 v184, v221, v184
	v_fmamk_f32 v228, v68, 0x3e38aa3b, v205
	v_exp_f32_e32 v225, v225
	v_add_f32_e32 v184, v222, v184
	v_fmamk_f32 v229, v69, 0x3e38aa3b, v205
	s_waitcnt lgkmcnt(0)
; #define SWRITE(b, i) do { *(LAS bf16x8*)(V_lds + (b) * SHM_V + vst0) = sr_[i].vs0; *(LAS bf16x8*)(V_lds + (b) * SHM_V + vst1) = sr_[i].vs1; \
;     _Pragma("unroll") for (int _c = 0; _c < NKC; ++_c) *(LAS bf16x8*)(K_lds + (b) * SHM_K + kswz<DQK>(krow[_c], kcol[_c] * 2)) = sr_[i].ks[_c]; } while (0)
; #define SWAIT() do { if constexpr (SDEPTH == 2) { if constexpr (NKC == 1) asm volatile("s_waitcnt vmcnt(3)" ::: "memory"); else if constexpr (NKC == 2) asm volatile("s_waitcnt vmcnt(4)" ::: "memory"); else asm volatile("s_waitcnt vmcnt(5)" ::: "memory"); } \
;     else asm volatile("s_waitcnt vmcnt(0)" ::: "memory"); } while (0)
; #define RESC(a) do { if (__any((a) < 1.f)) { if (hi == 0) al_l[r32] = (a); asm volatile("s_waitcnt lgkmcnt(0)" ::: "memory"); \
;     _Pragma("unroll") for (int d = 0; d < 4; ++d) _Pragma("unroll") for (int r = 0; r < 16; ++r) o[d][r] *= al_l[crow(r, hi)]; } } while (0)
; DI void partialSM(f32x16& p0, f32x16& p1, float& m_reg, float& mn, float& alpha, const float SCALE) {
;   const float C = SCALE * 1.4426950408889634f;
;   float pmax = p0[0];
; #pragma unroll
;   for (int r = 1; r < 16; ++r) pmax = fmaxf(pmax, p0[r]);
; #pragma unroll
;   for (int r = 0; r < 16; ++r) pmax = fmaxf(pmax, p1[r]);
;   { auto rr = __builtin_amdgcn_permlane32_swap(__float_as_uint(pmax), __float_as_uint(pmax), false, false);
;     pmax = fmaxf(__uint_as_float(rr[0]), __uint_as_float(rr[1])); }
;   if (__builtin_expect(__all(pmax - m_reg <= THR / SCALE), 1)) { mn = m_reg; alpha = 1.f; }
;   else { mn = fmaxf(m_reg, pmax); alpha = __builtin_amdgcn_exp2f((m_reg - mn) * C); m_reg = mn; }
;   const float mnC = -mn * C;
; #pragma unroll
;   for (int r = 0; r < 16; ++r) p0[r] = fmaf(p0[r], C, mnC);
; #pragma unroll
;   for (int r = 0; r < 16; ++r) p1[r] = fmaf(p1[r], C, mnC);
; #pragma unroll
;   for (int r = 0; r < 16; ++r) p0[r] = __builtin_amdgcn_exp2f(p0[r]);
; }
; template <int DQK, int SDEPTH, bool OUT_BF16, int QREG = DQK / 16, bool OUT_F16 = false> ...
;     ...
;     pv_d0(o, vb0 + SHM_V, pa0, pa1, pa2, pa3); partialSM(pA0, pA1, m_reg, mnA, alA, SCALE);
;     __syncthreads(); SWAIT(); SWRITE(1, SO);
;     RESC(alA); __syncthreads();
	v_mfma_f32_32x32x16_bf16 v[34:49], v[138:141], v[162:165], v[34:49]
	ds_read_b64_tr_b16 v[162:163], v169 offset:0x600
	ds_read_b64_tr_b16 v[164:165], v169 offset:0xe00
	v_exp_f32_e32 v226, v226
	v_add_f32_e32 v184, v223, v184
	v_fmamk_f32 v230, v70, 0x3e38aa3b, v205
	v_exp_f32_e32 v227, v227
	v_add_f32_e32 v184, v224, v184
	v_fmamk_f32 v231, v71, 0x3e38aa3b, v205
	v_exp_f32_e32 v228, v228
	v_mfma_f32_32x32x16_bf16 v[34:49], v[142:145], v[186:189], v[34:49]
	ds_read_b64_tr_b16 v[186:187], v169 offset:0x1600
	ds_read_b64_tr_b16 v[188:189], v169 offset:0x1e00
	v_add_f32_e32 v184, v225, v184
	v_fmamk_f32 v244, v72, 0x3e38aa3b, v205
	v_exp_f32_e32 v229, v229
	v_add_f32_e32 v184, v226, v184
	v_fmamk_f32 v245, v73, 0x3e38aa3b, v205
	v_exp_f32_e32 v230, v230
	v_mfma_f32_32x32x16_bf16 v[34:49], v[146:149], v[190:193], v[34:49]
	ds_read_b64_tr_b16 v[190:191], v169 offset:0x2600
	ds_read_b64_tr_b16 v[192:193], v169 offset:0x2e00
	v_add_f32_e32 v184, v227, v184
	v_fmamk_f32 v246, v74, 0x3e38aa3b, v205
	v_exp_f32_e32 v231, v231
	v_add_f32_e32 v184, v228, v184
	v_fmamk_f32 v247, v75, 0x3e38aa3b, v205
	v_exp_f32_e32 v244, v244
	v_mfma_f32_32x32x16_bf16 v[34:49], v[150:153], v[194:197], v[34:49]
	ds_read_b64_tr_b16 v[194:195], v169 offset:0x3600
	ds_read_b64_tr_b16 v[196:197], v169 offset:0x3e00
	v_add_f32_e32 v184, v229, v184
	v_fmamk_f32 v248, v76, 0x3e38aa3b, v205
	v_exp_f32_e32 v245, v245
	v_add_f32_e32 v184, v230, v184
	v_fmamk_f32 v249, v77, 0x3e38aa3b, v205
	v_exp_f32_e32 v246, v246
	s_waitcnt lgkmcnt(0)
	v_mfma_f32_32x32x16_bf16 v[18:33], v[138:141], v[162:165], v[18:33]
	v_add_f32_e32 v184, v231, v184
	v_fmamk_f32 v250, v78, 0x3e38aa3b, v205
	v_exp_f32_e32 v247, v247
	v_add_f32_e32 v184, v244, v184
	v_fmamk_f32 v251, v79, 0x3e38aa3b, v205
	v_exp_f32_e32 v248, v248
	v_mfma_f32_32x32x16_bf16 v[18:33], v[142:145], v[186:189], v[18:33]
	v_add_f32_e32 v184, v245, v184
	v_fmamk_f32 v252, v80, 0x3e38aa3b, v205
	v_exp_f32_e32 v249, v249
	v_add_f32_e32 v184, v246, v184
	v_fmamk_f32 v202, v81, 0x3e38aa3b, v205
	v_exp_f32_e32 v250, v250
	v_mfma_f32_32x32x16_bf16 v[18:33], v[146:149], v[190:193], v[18:33]
	v_add_f32_e32 v184, v247, v184
	v_exp_f32_e32 v251, v251
	v_add_f32_e32 v184, v248, v184
	v_exp_f32_e32 v252, v252
	v_add_f32_e32 v184, v249, v184
	v_exp_f32_e32 v202, v202
	v_mfma_f32_32x32x16_bf16 v[18:33], v[150:153], v[194:197], v[18:33]
	v_add_f32_e32 v184, v250, v184
	v_add_f32_e32 v184, v251, v184
	v_add_f32_e32 v184, v252, v184
	v_add_f32_e32 v184, v202, v184
	v_cmp_nge_f32_e32 vcc, 0x453a4f54, v184
	v_add_f32_e32 v170, v207, v184
	v_mov_b32_e32 v143, 1.0
	s_barrier
	s_waitcnt vmcnt(3)
	s_waitcnt vmcnt(2)
	ds_write_b128 v172, v[126:129] offset:16384
	s_waitcnt vmcnt(1)
	ds_write_b128 v173, v[130:133] offset:16384
	s_waitcnt vmcnt(0)
	ds_write_b128 v174, v[134:137] offset:40960
	s_cbranch_vccz .LBB0_792
	v_max3_f32 v203, v82, v83, v84
	v_max3_f32 v204, v85, v86, v87
	v_max3_f32 v203, v203, v88, v89
	v_max3_f32 v204, v204, v90, v91
	v_max3_f32 v203, v203, v92, v93
	v_max3_f32 v204, v204, v94, v95
	v_max3_f32 v203, v203, v96, v97
	v_max3_f32 v204, v204, v66, v67
	v_max3_f32 v203, v203, v68, v69
	v_max3_f32 v204, v204, v70, v71
	v_max3_f32 v203, v203, v72, v73
	v_max3_f32 v204, v204, v74, v75
	v_max3_f32 v203, v203, v76, v77
	v_max3_f32 v204, v204, v78, v79
	v_max3_f32 v203, v203, v80, v81
	v_max_f32_e32 v203, v203, v204
	v_mov_b32_e32 v204, v203
	s_nop 1
	v_permlane32_swap_b32_e32 v203, v204
	v_max_f32_e32 v203, v203, v204
	v_max_f32_e32 v203, v206, v203
	v_sub_f32_e32 v204, v206, v203
	v_mul_f32_e32 v204, 0x3e38aa3b, v204
	v_exp_f32_e32 v143, v204
	v_mov_b32_e32 v206, v203
	v_mul_f32_e32 v205, 0xbe38aa3b, v203
	v_fmamk_f32 v208, v82, 0x3e38aa3b, v205
	v_fmamk_f32 v209, v83, 0x3e38aa3b, v205
	v_fmamk_f32 v210, v84, 0x3e38aa3b, v205
	v_fmamk_f32 v211, v85, 0x3e38aa3b, v205
	v_fmamk_f32 v214, v86, 0x3e38aa3b, v205
	v_fmamk_f32 v215, v87, 0x3e38aa3b, v205
	v_fmamk_f32 v216, v88, 0x3e38aa3b, v205
	v_fmamk_f32 v217, v89, 0x3e38aa3b, v205
	v_fmamk_f32 v218, v90, 0x3e38aa3b, v205
	v_fmamk_f32 v219, v91, 0x3e38aa3b, v205
	v_fmamk_f32 v220, v92, 0x3e38aa3b, v205
	v_fmamk_f32 v221, v93, 0x3e38aa3b, v205
	v_fmamk_f32 v222, v94, 0x3e38aa3b, v205
	v_fmamk_f32 v223, v95, 0x3e38aa3b, v205
	v_fmamk_f32 v224, v96, 0x3e38aa3b, v205
	v_fmamk_f32 v225, v97, 0x3e38aa3b, v205
	v_fmamk_f32 v226, v66, 0x3e38aa3b, v205
	v_fmamk_f32 v227, v67, 0x3e38aa3b, v205
	v_fmamk_f32 v228, v68, 0x3e38aa3b, v205
	v_fmamk_f32 v229, v69, 0x3e38aa3b, v205
	v_fmamk_f32 v230, v70, 0x3e38aa3b, v205
	v_fmamk_f32 v231, v71, 0x3e38aa3b, v205
	v_fmamk_f32 v244, v72, 0x3e38aa3b, v205
	v_fmamk_f32 v245, v73, 0x3e38aa3b, v205
	v_fmamk_f32 v246, v74, 0x3e38aa3b, v205
	v_fmamk_f32 v247, v75, 0x3e38aa3b, v205
	v_fmamk_f32 v248, v76, 0x3e38aa3b, v205
	v_fmamk_f32 v249, v77, 0x3e38aa3b, v205
	v_fmamk_f32 v250, v78, 0x3e38aa3b, v205
	v_fmamk_f32 v251, v79, 0x3e38aa3b, v205
	v_fmamk_f32 v252, v80, 0x3e38aa3b, v205
	v_fmamk_f32 v202, v81, 0x3e38aa3b, v205
	v_exp_f32_e32 v208, v208
	v_exp_f32_e32 v209, v209
	v_exp_f32_e32 v210, v210
	v_exp_f32_e32 v211, v211
	v_exp_f32_e32 v214, v214
	v_exp_f32_e32 v215, v215
	v_exp_f32_e32 v216, v216
	v_exp_f32_e32 v217, v217
	v_exp_f32_e32 v218, v218
	v_exp_f32_e32 v219, v219
	v_exp_f32_e32 v220, v220
	v_exp_f32_e32 v221, v221
	v_exp_f32_e32 v222, v222
	v_exp_f32_e32 v223, v223
	v_exp_f32_e32 v224, v224
	v_exp_f32_e32 v225, v225
	v_exp_f32_e32 v226, v226
	v_exp_f32_e32 v227, v227
	v_exp_f32_e32 v228, v228
	v_exp_f32_e32 v229, v229
	v_exp_f32_e32 v230, v230
	v_exp_f32_e32 v231, v231
	v_exp_f32_e32 v244, v244
	v_exp_f32_e32 v245, v245
	v_exp_f32_e32 v246, v246
	v_exp_f32_e32 v247, v247
	v_exp_f32_e32 v248, v248
	v_exp_f32_e32 v249, v249
	v_exp_f32_e32 v250, v250
	v_exp_f32_e32 v251, v251
	v_exp_f32_e32 v252, v252
	v_exp_f32_e32 v202, v202
	v_add_f32_e32 v184, v208, v209
	v_add_f32_e32 v184, v210, v184
	v_add_f32_e32 v184, v211, v184
	v_add_f32_e32 v184, v214, v184
	v_add_f32_e32 v184, v215, v184
	v_add_f32_e32 v184, v216, v184
	v_add_f32_e32 v184, v217, v184
	v_add_f32_e32 v184, v218, v184
	v_add_f32_e32 v184, v219, v184
	v_add_f32_e32 v184, v220, v184
	v_add_f32_e32 v184, v221, v184
	v_add_f32_e32 v184, v222, v184
	v_add_f32_e32 v184, v223, v184
	v_add_f32_e32 v184, v224, v184
	v_add_f32_e32 v184, v225, v184
	v_add_f32_e32 v184, v226, v184
	v_add_f32_e32 v184, v227, v184
	v_add_f32_e32 v184, v228, v184
	v_add_f32_e32 v184, v229, v184
	v_add_f32_e32 v184, v230, v184
	v_add_f32_e32 v184, v231, v184
	v_add_f32_e32 v184, v244, v184
	v_add_f32_e32 v184, v245, v184
	v_add_f32_e32 v184, v246, v184
	v_add_f32_e32 v184, v247, v184
	v_add_f32_e32 v184, v248, v184
	v_add_f32_e32 v184, v249, v184
	v_add_f32_e32 v184, v250, v184
	v_add_f32_e32 v184, v251, v184
	v_add_f32_e32 v184, v252, v184
	v_add_f32_e32 v184, v202, v184
	v_fma_f32 v170, v143, v207, v184
	s_and_saveexec_b64 s[12:13], s[0:1]
	ds_write_b32 v168, v143 offset:49280
	s_or_b64 exec, exec, s[12:13]
	s_waitcnt lgkmcnt(0)
; #define SBAR() __builtin_amdgcn_sched_barrier(0)
; #define RESC(a) do { if (__any((a) < 1.f)) { if (hi == 0) al_l[r32] = (a); asm volatile("s_waitcnt lgkmcnt(0)" ::: "memory"); \
;     _Pragma("unroll") for (int d = 0; d < 4; ++d) _Pragma("unroll") for (int r = 0; r < 16; ++r) o[d][r] *= al_l[crow(r, hi)]; } } while (0)
; template <int DQK, int SDEPTH, bool OUT_BF16, int QREG = DQK / 16, bool OUT_F16 = false> ...
;     ...
;     RESC(alA); __syncthreads();
;   }
;   SBAR(); QKT(pB0, pB1, K_lds + SHM_K);
;   finishSM(pA0, pA1, alA, l_reg, pa0, pa1, pa2, pa3); SBAR();
;   pv_d0(o, vb0, pa0, pa1, pa2, pa3); partialSM(pB0, pB1, m_reg, mnB, alB, SCALE);
;   __syncthreads(); RESC(alB);
;   finishSM(pB0, pB1, alB, l_reg, pa0, pa1, pa2, pa3); SBAR();
	v_add_u32_e32 v139, v157, v0
	ds_read_b128 v[126:129], v139 offset:49376
	ds_read_b128 v[130:133], v139 offset:49344
	ds_read_b128 v[134:137], v139 offset:49312
	ds_read_b128 v[144:147], v139 offset:49280
	s_waitcnt lgkmcnt(3)
	v_pk_mul_f32 v[14:15], v[14:15], v[126:127]
	s_waitcnt lgkmcnt(2)
	v_pk_mul_f32 v[10:11], v[10:11], v[130:131]
	s_waitcnt lgkmcnt(1)
	v_pk_mul_f32 v[6:7], v[6:7], v[134:135]
	v_pk_mul_f32 v[16:17], v[16:17], v[128:129]
	v_pk_mul_f32 v[12:13], v[12:13], v[132:133]
	v_pk_mul_f32 v[8:9], v[8:9], v[136:137]
	s_waitcnt lgkmcnt(0)
	v_pk_mul_f32 v[4:5], v[4:5], v[146:147]
	v_pk_mul_f32 v[2:3], v[2:3], v[144:145]
	v_pk_mul_f32 v[62:63], v[62:63], v[126:127]
	v_pk_mul_f32 v[58:59], v[58:59], v[130:131]
	v_pk_mul_f32 v[54:55], v[54:55], v[134:135]
	v_pk_mul_f32 v[64:65], v[64:65], v[128:129]
	v_pk_mul_f32 v[60:61], v[60:61], v[132:133]
	v_pk_mul_f32 v[56:57], v[56:57], v[136:137]
	v_pk_mul_f32 v[52:53], v[52:53], v[146:147]
	v_pk_mul_f32 v[50:51], v[50:51], v[144:145]
	v_pk_mul_f32 v[46:47], v[46:47], v[126:127]
	v_pk_mul_f32 v[42:43], v[42:43], v[130:131]
	v_pk_mul_f32 v[38:39], v[38:39], v[134:135]
	v_pk_mul_f32 v[48:49], v[48:49], v[128:129]
	v_pk_mul_f32 v[44:45], v[44:45], v[132:133]
	v_pk_mul_f32 v[40:41], v[40:41], v[136:137]
	v_pk_mul_f32 v[36:37], v[36:37], v[146:147]
	v_pk_mul_f32 v[34:35], v[34:35], v[144:145]
	v_pk_mul_f32 v[30:31], v[30:31], v[126:127]
	v_pk_mul_f32 v[26:27], v[26:27], v[130:131]
	v_pk_mul_f32 v[22:23], v[22:23], v[134:135]
	v_pk_mul_f32 v[32:33], v[32:33], v[128:129]
	v_pk_mul_f32 v[28:29], v[28:29], v[132:133]
	v_pk_mul_f32 v[24:25], v[24:25], v[136:137]
	v_pk_mul_f32 v[20:21], v[20:21], v[146:147]
	v_pk_mul_f32 v[18:19], v[18:19], v[144:145]
.LBB0_792:
	v_lshl_add_u64 v[158:159], v[158:159], 0, s[54:55]
	s_mov_b64 s[2:3], 0x4000
	v_lshl_add_u64 v[160:161], v[160:161], 0, s[2:3]
	s_add_i32 s46, s46, 2
	s_and_b64 vcc, exec, s[10:11]
	s_waitcnt lgkmcnt(0)
	s_barrier
	s_cbranch_vccnz .Ldiff_loop_exit
	s_branch .LBB0_782
.Ldiff_loop_exit:
	v_mov_b32_e32 v146, v208
	v_mov_b32_e32 v148, v209
	v_mov_b32_e32 v150, v210
	v_mov_b32_e32 v152, v211
	v_mov_b32_e32 v162, v214
	v_mov_b32_e32 v164, v215
	v_mov_b32_e32 v165, v216
	v_mov_b32_e32 v186, v217
	v_mov_b32_e32 v144, v218
	v_mov_b32_e32 v145, v219
	v_mov_b32_e32 v147, v220
	v_mov_b32_e32 v149, v221
	v_mov_b32_e32 v151, v222
	v_mov_b32_e32 v153, v223
	v_mov_b32_e32 v163, v224
	v_mov_b32_e32 v183, v225
	v_mov_b32_e32 v140, v226
	v_mov_b32_e32 v141, v227
	v_mov_b32_e32 v138, v228
	v_mov_b32_e32 v139, v229
	v_mov_b32_e32 v134, v230
	v_mov_b32_e32 v135, v231
	v_mov_b32_e32 v130, v244
	v_mov_b32_e32 v131, v245
	v_mov_b32_e32 v128, v246
	v_mov_b32_e32 v129, v247
	v_mov_b32_e32 v136, v248
	v_mov_b32_e32 v137, v249
	v_mov_b32_e32 v132, v250
	v_mov_b32_e32 v133, v251
	v_mov_b32_e32 v126, v252
	v_mov_b32_e32 v127, v202
	v_mov_b32_e32 v142, v206
	v_mov_b32_e32 v170, v207
	v_mov_b32_e32 v203, v207
	s_nop 1
	v_permlane32_swap_b32_e32 v170, v203
	v_add_f32_e32 v170, v170, v203
